# proj0 epilogue: rope cos/sin table rows preloaded at tile start into unused VGPRs (3 of 4 sets), on top of deeper pass-1 prefetch + bulk x1 stores
# speedup vs baseline: 1.0621x; 1.0026x over previous
.LBB0_147:
	s_cmp_lt_u32 s62, 8
	s_cbranch_scc0 .Lp0_nopre
	v_lshrrev_b32_e32 v192, 7, v144
	v_and_b32_e32 v193, 31, v144
	v_lshl_add_u32 v192, v192, 6, v193
	v_mov_b32_e32 v194, s4
	v_lshl_add_u32 v192, v194, 8, v192
	v_bfe_u32 v193, v144, 5, 1
	v_lshlrev_b32_e32 v193, 6, v193
	v_lshl_add_u32 v192, v192, 8, v193
	v_add_u32_e32 v193, 0x2000, v192
	global_load_dwordx4 v[196:199], v192, s[0:1] offset:0
	global_load_dwordx4 v[200:203], v192, s[0:1] offset:16
	global_load_dwordx4 v[204:207], v192, s[0:1] offset:32
	global_load_dwordx4 v[208:211], v192, s[0:1] offset:48
	global_load_dwordx4 v[212:215], v192, s[0:1] offset:128
	global_load_dwordx4 v[216:219], v192, s[0:1] offset:144
	global_load_dwordx4 v[220:223], v192, s[0:1] offset:160
	global_load_dwordx4 v[224:227], v192, s[0:1] offset:176
	global_load_dwordx4 v[228:231], v193, s[0:1] offset:0
	global_load_dwordx4 v[232:235], v193, s[0:1] offset:16
	global_load_dwordx4 v[238:241], v193, s[0:1] offset:32
	global_load_dwordx4 v[242:245], v193, s[0:1] offset:48

.LBB0_153:
	s_lshl_b32 s35, s4, 8
	v_lshlrev_b32_e32 v163, 3, v150
	v_add_u32_e32 v150, s35, v161
	v_ashrrev_i32_e32 v151, 31, v150
	v_lshlrev_b64 v[96:97], 5, v[150:151]
	s_andn2_b64 vcc, exec, s[2:3]
	v_or_b32_e32 v96, v96, v163
	s_cbranch_vccnz .LBB0_158
	s_cmp_eq_u32 s61, 1
	s_cbranch_scc0 .LBB0_156
	v_lshl_add_u64 v[122:123], v[96:97], 3, s[0:1]
	v_mov_b32_e32 v138, v196
	v_mov_b32_e32 v139, v197
	v_mov_b32_e32 v140, v198
	v_mov_b32_e32 v141, v199
	v_mov_b32_e32 v146, v200
	v_mov_b32_e32 v147, v201
	v_mov_b32_e32 v148, v202
	v_mov_b32_e32 v149, v203
	v_mov_b32_e32 v152, v204
	v_mov_b32_e32 v153, v205
	v_mov_b32_e32 v154, v206
	v_mov_b32_e32 v155, v207
	v_mov_b32_e32 v164, v208
	v_mov_b32_e32 v165, v209
	v_mov_b32_e32 v166, v210
	v_mov_b32_e32 v167, v211
	v_mov_b32_e32 v156, v134
	v_mov_b32_e32 v157, v133
	v_mov_b32_e32 v122, v132
	v_mov_b32_e32 v123, v135
	v_mov_b32_e32 v170, v136
	v_mov_b32_e32 v171, v113
	v_mov_b32_e32 v174, v120
	v_mov_b32_e32 v175, v115
	v_mov_b32_e32 v168, v112
	v_mov_b32_e32 v169, v137
	v_mov_b32_e32 v172, v114
	v_mov_b32_e32 v173, v121
	v_mov_b32_e32 v178, v139
	v_mov_b32_e32 v179, v141
	v_mov_b32_e32 v176, v138
	v_pk_mul_f32 v[142:143], v[142:143], v[166:167]
	v_pk_mul_f32 v[106:107], v[106:107], v[166:167]
	v_mov_b32_e32 v177, v140
	v_mov_b32_e32 v180, v139
	v_mov_b32_e32 v139, v141
	v_mov_b32_e32 v182, v147
	v_mov_b32_e32 v183, v149
	v_mov_b32_e32 v184, v147
	v_mov_b32_e32 v147, v149
	v_mov_b32_e32 v149, v154
	v_mov_b32_e32 v186, v153
	v_mov_b32_e32 v187, v155
	v_mov_b32_e32 v188, v153
	v_mov_b32_e32 v189, v154
	v_mov_b32_e32 v153, v155
	v_mul_f32_e32 v154, v98, v164
	v_mul_f32_e32 v190, v104, v165
	v_mul_f32_e32 v104, v104, v164
	v_mul_f32_e32 v98, v98, v165
	v_pk_mul_f32 v[156:157], v[156:157], v[178:179]
	v_mov_b32_e32 v155, v142
	v_mov_b32_e32 v191, v143
	v_mov_b32_e32 v105, v106
	v_mov_b32_e32 v99, v107
	v_mov_b32_e32 v181, v140
	v_mov_b32_e32 v140, v146
	v_mov_b32_e32 v141, v148
	v_mov_b32_e32 v185, v148
	v_mov_b32_e32 v148, v152
	v_pk_mul_f32 v[134:135], v[134:135], v[138:139]
	v_pk_mul_f32 v[138:139], v[170:171], v[182:183]
	v_pk_mul_f32 v[136:137], v[136:137], v[146:147]
	v_pk_mul_f32 v[146:147], v[174:175], v[186:187]
	v_pk_mul_f32 v[120:121], v[120:121], v[152:153]
	v_pk_fma_f32 v[122:123], v[122:123], v[176:177], v[156:157] neg_lo:[0,0,1] neg_hi:[0,0,1]
	v_pk_add_f32 v[154:155], v[154:155], v[190:191] neg_lo:[0,1] neg_hi:[0,1]
	v_pk_add_f32 v[156:157], v[104:105], v[98:99]
	v_pk_fma_f32 v[140:141], v[168:169], v[140:141], v[138:139] neg_lo:[0,0,1] neg_hi:[0,0,1]
	v_pk_fma_f32 v[148:149], v[172:173], v[148:149], v[146:147] neg_lo:[0,0,1] neg_hi:[0,0,1]
	v_pk_fma_f32 v[138:139], v[132:133], v[180:181], v[134:135]
	v_pk_fma_f32 v[146:147], v[112:113], v[184:185], v[136:137]
	v_pk_fma_f32 v[152:153], v[114:115], v[188:189], v[120:121]
	v_mov_b32_e32 v98, v154
	v_mov_b32_e32 v104, v156
	s_branch .LBB0_157

.LBB0_166:
	v_add3_u32 v116, v161, s35, 32
	v_ashrrev_i32_e32 v117, 31, v116
	v_lshlrev_b64 v[64:65], 5, v[116:117]
	s_andn2_b64 vcc, exec, s[4:5]
	v_or_b32_e32 v64, v64, v163
	s_cbranch_vccnz .LBB0_174
	s_cmp_eq_u32 s61, 1
	s_cbranch_scc0 .LBB0_172
	v_lshl_add_u64 v[90:91], v[64:65], 3, s[0:1]
	v_mov_b32_e32 v112, v228
	v_mov_b32_e32 v113, v229
	v_mov_b32_e32 v114, v230
	v_mov_b32_e32 v115, v231
	v_mov_b32_e32 v118, v232
	v_mov_b32_e32 v119, v233
	v_mov_b32_e32 v120, v234
	v_mov_b32_e32 v121, v235
	v_mov_b32_e32 v122, v238
	v_mov_b32_e32 v123, v239
	v_mov_b32_e32 v124, v240
	v_mov_b32_e32 v125, v241
	v_mov_b32_e32 v132, v242
	v_mov_b32_e32 v133, v243
	v_mov_b32_e32 v134, v244
	v_mov_b32_e32 v135, v245
	v_mov_b32_e32 v108, v102
	v_mov_b32_e32 v109, v101
	v_mov_b32_e32 v136, v106
	v_mov_b32_e32 v137, v81
	v_mov_b32_e32 v140, v88
	v_mov_b32_e32 v141, v83
	v_mov_b32_e32 v90, v100
	v_mov_b32_e32 v91, v103
	v_mov_b32_e32 v126, v80
	v_mov_b32_e32 v127, v107
	v_mov_b32_e32 v138, v82
	v_mov_b32_e32 v139, v89
	v_mov_b32_e32 v146, v113
	v_mov_b32_e32 v147, v115
	v_mov_b32_e32 v148, v113
	v_pk_mul_f32 v[110:111], v[110:111], v[134:135]
	v_pk_mul_f32 v[74:75], v[74:75], v[134:135]
	v_mov_b32_e32 v113, v115
	v_mov_b32_e32 v150, v119
	v_mov_b32_e32 v151, v121
	v_mov_b32_e32 v152, v119
	v_mov_b32_e32 v119, v121
	v_mov_b32_e32 v121, v124
	v_mov_b32_e32 v154, v123
	v_mov_b32_e32 v155, v125
	v_mov_b32_e32 v156, v123
	v_mov_b32_e32 v157, v124
	v_mov_b32_e32 v123, v125
	v_mul_f32_e32 v124, v66, v132
	v_mul_f32_e32 v164, v72, v133
	v_mul_f32_e32 v72, v72, v132
	v_mul_f32_e32 v66, v66, v133
	v_mov_b32_e32 v125, v110
	v_mov_b32_e32 v165, v111
	v_mov_b32_e32 v73, v74
	v_mov_b32_e32 v67, v75
	v_mov_b32_e32 v142, v112
	v_mov_b32_e32 v143, v114
	v_mov_b32_e32 v149, v114
	v_mov_b32_e32 v114, v118
	v_mov_b32_e32 v115, v120
	v_mov_b32_e32 v153, v120
	v_mov_b32_e32 v120, v122
	v_pk_mul_f32 v[108:109], v[108:109], v[146:147]
	v_pk_mul_f32 v[102:103], v[102:103], v[112:113]
	v_pk_mul_f32 v[112:113], v[136:137], v[150:151]
	v_pk_mul_f32 v[106:107], v[106:107], v[118:119]
	v_pk_mul_f32 v[118:119], v[140:141], v[154:155]
	v_pk_mul_f32 v[88:89], v[88:89], v[122:123]
	v_pk_add_f32 v[122:123], v[124:125], v[164:165] neg_lo:[0,1] neg_hi:[0,1]
	v_pk_add_f32 v[124:125], v[72:73], v[66:67]
	v_pk_fma_f32 v[90:91], v[90:91], v[142:143], v[108:109] neg_lo:[0,0,1] neg_hi:[0,0,1]
	v_pk_fma_f32 v[112:113], v[126:127], v[114:115], v[112:113] neg_lo:[0,0,1] neg_hi:[0,0,1]
	v_pk_fma_f32 v[118:119], v[138:139], v[120:121], v[118:119] neg_lo:[0,0,1] neg_hi:[0,0,1]
	v_pk_fma_f32 v[108:109], v[100:101], v[148:149], v[102:103]
	v_pk_fma_f32 v[114:115], v[80:81], v[152:153], v[106:107]
	v_pk_fma_f32 v[120:121], v[82:83], v[156:157], v[88:89]
	v_mov_b32_e32 v66, v122
	v_mov_b32_e32 v72, v124
	s_branch .LBB0_173

.LBB0_170:
	s_cmp_eq_u32 s61, 1
	s_cbranch_scc0 .LBB0_218
	v_lshl_add_u64 v[140:141], v[96:97], 3, s[0:1]
	v_mov_b32_e32 v122, v212
	v_mov_b32_e32 v123, v213
	v_mov_b32_e32 v124, v214
	v_mov_b32_e32 v125, v215
	v_mov_b32_e32 v132, v216
	v_mov_b32_e32 v133, v217
	v_mov_b32_e32 v134, v218
	v_mov_b32_e32 v135, v219
	v_mov_b32_e32 v136, v220
	v_mov_b32_e32 v137, v221
	v_mov_b32_e32 v138, v222
	v_mov_b32_e32 v139, v223
	s_nop 0
	v_mov_b32_e32 v140, v224
	v_mov_b32_e32 v141, v225
	v_mov_b32_e32 v142, v226
	v_mov_b32_e32 v143, v227
	v_mov_b32_e32 v148, v120
	v_mov_b32_e32 v149, v113
	v_mov_b32_e32 v152, v118
	v_mov_b32_e32 v153, v115
	v_mov_b32_e32 v146, v112
	v_mov_b32_e32 v147, v121
	v_mov_b32_e32 v150, v114
	v_mov_b32_e32 v151, v119
	v_mov_b32_e32 v156, v108
	v_mov_b32_e32 v157, v117
	v_mov_b32_e32 v154, v116
	v_mov_b32_e32 v155, v109
	v_mov_b32_e32 v166, v123
	v_mov_b32_e32 v167, v125
	v_mov_b32_e32 v170, v133
	v_mov_b32_e32 v171, v135
	v_pk_mul_f32 v[126:127], v[126:127], v[142:143]
	v_pk_mul_f32 v[110:111], v[110:111], v[142:143]
	v_mov_b32_e32 v164, v122
	v_mov_b32_e32 v165, v124
	v_mov_b32_e32 v168, v123
	v_mov_b32_e32 v169, v124
	v_mov_b32_e32 v123, v125
	v_mov_b32_e32 v124, v132
	v_mov_b32_e32 v125, v134
	v_mov_b32_e32 v172, v133
	v_mov_b32_e32 v133, v135
	v_mov_b32_e32 v135, v138
	v_mov_b32_e32 v174, v137
	v_mov_b32_e32 v175, v139
	v_mov_b32_e32 v176, v137
	v_mov_b32_e32 v177, v138
	v_mov_b32_e32 v137, v139
	v_mul_f32_e32 v138, v100, v140
	v_mul_f32_e32 v178, v102, v141
	v_mul_f32_e32 v102, v102, v140
	v_mul_f32_e32 v100, v100, v141
	v_pk_mul_f32 v[140:141], v[148:149], v[166:167]
	v_pk_mul_f32 v[142:143], v[152:153], v[170:171]
	v_mov_b32_e32 v139, v126
	v_mov_b32_e32 v179, v127
	v_mov_b32_e32 v103, v110
	v_mov_b32_e32 v101, v111
	v_mov_b32_e32 v173, v134
	v_mov_b32_e32 v134, v136
	v_pk_mul_f32 v[120:121], v[120:121], v[122:123]
	v_pk_mul_f32 v[118:119], v[118:119], v[132:133]
	v_pk_mul_f32 v[148:149], v[156:157], v[174:175]
	v_pk_mul_f32 v[108:109], v[108:109], v[136:137]
	v_pk_fma_f32 v[122:123], v[146:147], v[164:165], v[140:141] neg_lo:[0,0,1] neg_hi:[0,0,1]
	v_pk_fma_f32 v[132:133], v[150:151], v[124:125], v[142:143] neg_lo:[0,0,1] neg_hi:[0,0,1]
	v_pk_add_f32 v[140:141], v[138:139], v[178:179] neg_lo:[0,1] neg_hi:[0,1]
	v_pk_add_f32 v[142:143], v[102:103], v[100:101]
	v_pk_fma_f32 v[136:137], v[154:155], v[134:135], v[148:149] neg_lo:[0,0,1] neg_hi:[0,0,1]
	v_pk_fma_f32 v[124:125], v[112:113], v[168:169], v[120:121]
	v_pk_fma_f32 v[134:135], v[114:115], v[172:173], v[118:119]
	v_pk_fma_f32 v[138:139], v[116:117], v[176:177], v[108:109]
	v_mov_b32_e32 v100, v140
	v_mov_b32_e32 v102, v142
	s_branch .LBB0_219

.LBB0_207:
	s_cmp_eq_u32 s61, 1
	s_cbranch_scc0 .LBB0_222
	v_lshl_add_u64 v[42:43], v[96:97], 3, s[0:1]
	v_mov_b32_e32 v78, v196
	v_mov_b32_e32 v79, v197
	v_mov_b32_e32 v80, v198
	v_mov_b32_e32 v81, v199
	v_mov_b32_e32 v82, v200
	v_mov_b32_e32 v83, v201
	v_mov_b32_e32 v84, v202
	v_mov_b32_e32 v85, v203
	v_mov_b32_e32 v86, v204
	v_mov_b32_e32 v87, v205
	v_mov_b32_e32 v88, v206
	v_mov_b32_e32 v89, v207
	v_mov_b32_e32 v90, v208
	v_mov_b32_e32 v91, v209
	v_mov_b32_e32 v92, v210
	v_mov_b32_e32 v93, v211
	v_mov_b32_e32 v94, v72
	v_mov_b32_e32 v95, v49
	v_mov_b32_e32 v102, v40
	v_mov_b32_e32 v103, v51
	v_mov_b32_e32 v43, v71
	v_mov_b32_e32 v58, v70
	v_mov_b32_e32 v59, v69
	v_mov_b32_e32 v74, v48
	v_mov_b32_e32 v75, v73
	v_mov_b32_e32 v100, v50
	v_mov_b32_e32 v101, v41
	v_mov_b32_e32 v42, v68
	v_mov_b32_e32 v106, v79
	v_mov_b32_e32 v108, v79
	v_mov_b32_e32 v79, v81
	v_mov_b32_e32 v110, v83
	v_mov_b32_e32 v111, v85
	v_mov_b32_e32 v112, v83
	v_mov_b32_e32 v83, v85
	v_mov_b32_e32 v114, v87
	v_mov_b32_e32 v115, v89
	v_pk_mul_f32 v[76:77], v[76:77], v[92:93]
	v_pk_mul_f32 v[56:57], v[56:57], v[92:93]
	v_mov_b32_e32 v104, v78
	v_mov_b32_e32 v105, v80
	v_mov_b32_e32 v107, v81
	v_mov_b32_e32 v109, v80
	v_mov_b32_e32 v80, v82
	v_mov_b32_e32 v81, v84
	v_mov_b32_e32 v113, v84
	v_mov_b32_e32 v84, v86
	v_mov_b32_e32 v85, v88
	v_mov_b32_e32 v116, v87
	v_mov_b32_e32 v117, v88
	v_mov_b32_e32 v87, v89
	v_mul_f32_e32 v88, v32, v90
	v_mul_f32_e32 v118, v34, v91
	v_mul_f32_e32 v34, v34, v90
	v_mul_f32_e32 v32, v32, v91
	v_pk_mul_f32 v[70:71], v[70:71], v[78:79]
	v_pk_mul_f32 v[78:79], v[94:95], v[110:111]
	v_pk_mul_f32 v[72:73], v[72:73], v[82:83]
	v_pk_mul_f32 v[82:83], v[102:103], v[114:115]
	v_mov_b32_e32 v89, v76
	v_mov_b32_e32 v119, v77
	v_mov_b32_e32 v35, v56
	v_mov_b32_e32 v33, v57
	v_pk_mul_f32 v[58:59], v[58:59], v[106:107]
	v_pk_mul_f32 v[40:41], v[40:41], v[86:87]
	v_pk_fma_f32 v[74:75], v[74:75], v[80:81], v[78:79] neg_lo:[0,0,1] neg_hi:[0,0,1]
	v_pk_fma_f32 v[80:81], v[100:101], v[84:85], v[82:83] neg_lo:[0,0,1] neg_hi:[0,0,1]
	v_pk_add_f32 v[84:85], v[88:89], v[118:119] neg_lo:[0,1] neg_hi:[0,1]
	v_pk_add_f32 v[86:87], v[34:35], v[32:33]
	v_pk_fma_f32 v[42:43], v[42:43], v[104:105], v[58:59] neg_lo:[0,0,1] neg_hi:[0,0,1]
	v_pk_fma_f32 v[58:59], v[68:69], v[108:109], v[70:71]
	v_pk_fma_f32 v[78:79], v[48:49], v[112:113], v[72:73]
	v_pk_fma_f32 v[82:83], v[50:51], v[116:117], v[40:41]
	v_mov_b32_e32 v32, v84
	v_mov_b32_e32 v34, v86
	s_branch .LBB0_223

.LBB0_210:
	s_cmp_eq_u32 s61, 1
	s_cbranch_scc0 .LBB0_224
	v_lshl_add_u64 v[72:73], v[96:97], 3, s[0:1]
	v_mov_b32_e32 v54, v212
	v_mov_b32_e32 v55, v213
	v_mov_b32_e32 v56, v214
	v_mov_b32_e32 v57, v215
	v_mov_b32_e32 v60, v216
	v_mov_b32_e32 v61, v217
	v_mov_b32_e32 v62, v218
	v_mov_b32_e32 v63, v219
	v_mov_b32_e32 v68, v220
	v_mov_b32_e32 v69, v221
	v_mov_b32_e32 v70, v222
	v_mov_b32_e32 v71, v223
	s_nop 0
	v_mov_b32_e32 v72, v224
	v_mov_b32_e32 v73, v225
	v_mov_b32_e32 v74, v226
	v_mov_b32_e32 v75, v227
	v_mov_b32_e32 v80, v50
	v_mov_b32_e32 v81, v41
	v_mov_b32_e32 v84, v52
	v_mov_b32_e32 v85, v43
	v_mov_b32_e32 v78, v40
	v_mov_b32_e32 v79, v51
	v_mov_b32_e32 v82, v42
	v_mov_b32_e32 v83, v53
	v_mov_b32_e32 v88, v44
	v_mov_b32_e32 v89, v49
	v_mov_b32_e32 v86, v48
	v_mov_b32_e32 v87, v45
	v_mov_b32_e32 v92, v55
	v_mov_b32_e32 v93, v57
	v_mov_b32_e32 v96, v61
	v_mov_b32_e32 v97, v63
	v_pk_mul_f32 v[58:59], v[58:59], v[74:75]
	v_pk_mul_f32 v[46:47], v[46:47], v[74:75]
	v_mov_b32_e32 v90, v54
	v_mov_b32_e32 v91, v56
	v_mov_b32_e32 v94, v55
	v_mov_b32_e32 v95, v56
	v_mov_b32_e32 v55, v57
	v_mov_b32_e32 v56, v60
	v_mov_b32_e32 v57, v62
	v_mov_b32_e32 v98, v61
	v_mov_b32_e32 v61, v63
	v_mov_b32_e32 v63, v70
	v_mov_b32_e32 v100, v69
	v_mov_b32_e32 v101, v71
	v_mov_b32_e32 v102, v69
	v_mov_b32_e32 v103, v70
	v_mov_b32_e32 v69, v71
	v_mul_f32_e32 v70, v36, v72
	v_mul_f32_e32 v104, v38, v73
	v_mul_f32_e32 v38, v38, v72
	v_mul_f32_e32 v36, v36, v73
	v_pk_mul_f32 v[72:73], v[80:81], v[92:93]
	v_pk_mul_f32 v[74:75], v[84:85], v[96:97]
	v_mov_b32_e32 v71, v58
	v_mov_b32_e32 v105, v59
	v_mov_b32_e32 v39, v46
	v_mov_b32_e32 v37, v47
	v_mov_b32_e32 v99, v62
	v_mov_b32_e32 v62, v68
	v_pk_mul_f32 v[50:51], v[50:51], v[54:55]
	v_pk_mul_f32 v[52:53], v[52:53], v[60:61]
	v_pk_mul_f32 v[80:81], v[88:89], v[100:101]
	v_pk_mul_f32 v[44:45], v[44:45], v[68:69]
	v_pk_fma_f32 v[54:55], v[78:79], v[90:91], v[72:73] neg_lo:[0,0,1] neg_hi:[0,0,1]
	v_pk_fma_f32 v[60:61], v[82:83], v[56:57], v[74:75] neg_lo:[0,0,1] neg_hi:[0,0,1]
	v_pk_add_f32 v[72:73], v[70:71], v[104:105] neg_lo:[0,1] neg_hi:[0,1]
	v_pk_add_f32 v[74:75], v[38:39], v[36:37]
	v_pk_fma_f32 v[68:69], v[86:87], v[62:63], v[80:81] neg_lo:[0,0,1] neg_hi:[0,0,1]
	v_pk_fma_f32 v[56:57], v[40:41], v[94:95], v[50:51]
	v_pk_fma_f32 v[62:63], v[42:43], v[98:99], v[52:53]
	v_pk_fma_f32 v[70:71], v[48:49], v[102:103], v[44:45]
	v_mov_b32_e32 v36, v72
	v_mov_b32_e32 v38, v74
	s_branch .LBB0_225

.LBB0_213:
	s_cmp_eq_u32 s61, 1
	s_cbranch_scc0 .LBB0_226
	v_lshl_add_u64 v[50:51], v[64:65], 3, s[0:1]
	v_mov_b32_e32 v24, v228
	v_mov_b32_e32 v25, v229
	v_mov_b32_e32 v26, v230
	v_mov_b32_e32 v27, v231
	v_mov_b32_e32 v42, v232
	v_mov_b32_e32 v43, v233
	v_mov_b32_e32 v44, v234
	v_mov_b32_e32 v45, v235
	v_mov_b32_e32 v46, v238
	v_mov_b32_e32 v47, v239
	v_mov_b32_e32 v48, v240
	v_mov_b32_e32 v49, v241
	s_nop 0
	v_mov_b32_e32 v50, v242
	v_mov_b32_e32 v51, v243
	v_mov_b32_e32 v52, v244
	v_mov_b32_e32 v53, v245
	v_mov_b32_e32 v56, v36
	v_mov_b32_e32 v57, v35
	v_mov_b32_e32 v60, v38
	v_mov_b32_e32 v61, v17
	v_mov_b32_e32 v54, v34
	v_mov_b32_e32 v55, v37
	v_mov_b32_e32 v58, v16
	v_mov_b32_e32 v59, v39
	v_mov_b32_e32 v68, v8
	v_mov_b32_e32 v69, v19
	v_mov_b32_e32 v62, v18
	v_mov_b32_e32 v63, v9
	v_mov_b32_e32 v72, v25
	v_mov_b32_e32 v73, v27
	v_mov_b32_e32 v78, v43
	v_mov_b32_e32 v79, v45
	v_pk_mul_f32 v[40:41], v[40:41], v[52:53]
	v_pk_mul_f32 v[10:11], v[10:11], v[52:53]
	v_mov_b32_e32 v70, v24
	v_mov_b32_e32 v71, v26
	v_mov_b32_e32 v74, v25
	v_mov_b32_e32 v75, v26
	v_mov_b32_e32 v25, v27
	v_mov_b32_e32 v26, v42
	v_mov_b32_e32 v27, v44
	v_mov_b32_e32 v80, v43
	v_mov_b32_e32 v43, v45
	v_mov_b32_e32 v45, v48
	v_mov_b32_e32 v82, v47
	v_mov_b32_e32 v83, v49
	v_mov_b32_e32 v84, v47
	v_mov_b32_e32 v85, v48
	v_mov_b32_e32 v47, v49
	v_mul_f32_e32 v48, v0, v50
	v_mul_f32_e32 v86, v2, v51
	v_mul_f32_e32 v2, v2, v50
	v_mul_f32_e32 v0, v0, v51
	v_pk_mul_f32 v[50:51], v[56:57], v[72:73]
	v_pk_mul_f32 v[52:53], v[60:61], v[78:79]
	v_mov_b32_e32 v49, v40
	v_mov_b32_e32 v87, v41
	v_mov_b32_e32 v3, v10
	v_mov_b32_e32 v1, v11
	v_mov_b32_e32 v81, v44
	v_mov_b32_e32 v44, v46
	v_pk_mul_f32 v[36:37], v[36:37], v[24:25]
	v_pk_mul_f32 v[38:39], v[38:39], v[42:43]
	v_pk_mul_f32 v[56:57], v[68:69], v[82:83]
	v_pk_mul_f32 v[8:9], v[8:9], v[46:47]
	v_pk_fma_f32 v[24:25], v[54:55], v[70:71], v[50:51] neg_lo:[0,0,1] neg_hi:[0,0,1]
	v_pk_fma_f32 v[42:43], v[58:59], v[26:27], v[52:53] neg_lo:[0,0,1] neg_hi:[0,0,1]
	v_pk_add_f32 v[50:51], v[48:49], v[86:87] neg_lo:[0,1] neg_hi:[0,1]
	v_pk_add_f32 v[52:53], v[2:3], v[0:1]
	v_pk_fma_f32 v[46:47], v[62:63], v[44:45], v[56:57] neg_lo:[0,0,1] neg_hi:[0,0,1]
	v_pk_fma_f32 v[26:27], v[34:35], v[74:75], v[36:37]
	v_pk_fma_f32 v[44:45], v[16:17], v[80:81], v[38:39]
	v_pk_fma_f32 v[48:49], v[18:19], v[84:85], v[8:9]
	v_mov_b32_e32 v0, v50
	v_mov_b32_e32 v2, v52
	s_branch .LBB0_227

.LBB0_390:
	s_lshl_b32 s34, s15, 8
	v_mov_b32 v128, 0
	s_add_i32 s82, s57, s34
	v_lshlrev_b32_e32 v154, 3, v132
	v_or_b32_e32 v128, s2, v154
	s_ashr_i32 s2, s82, 13
	s_mul_i32 s34, s2, 0xc00
	s_ashr_i32 s35, s34, 31
	s_ashr_i32 s83, s82, 31
	s_lshl_b64 s[34:35], s[34:35], 2
	v_or_b32_e32 v136, s58, v128
	s_add_u32 s58, s28, s34
	v_or_b32_e32 v140, s82, v152
	s_addc_u32 s59, s29, s35
	v_ashrrev_i32_e32 v141, 31, v140
	v_lshl_add_u64 v[128:129], v[136:137], 2, s[58:59]
	v_lshlrev_b64 v[130:131], 10, v[140:141]
	s_movk_i32 s2, 0x2000
	v_lshl_add_u64 v[130:131], v[130:131], 0, v[136:137]
	v_add_co_u32_e32 v146, vcc, s2, v128
	v_lshlrev_b64 v[148:149], 2, v[130:131]
	s_nop 0
	v_addc_co_u32_e32 v147, vcc, 0, v129, vcc
	v_lshl_add_u64 v[142:143], v[128:129], 0, s[6:7]
	v_lshl_add_u64 v[138:139], s[36:37], 0, v[148:149]
	global_load_dwordx4 v[212:215], v[146:147], off
	global_load_dwordx4 v[216:219], v[138:139], off offset:16
	global_load_dwordx4 v[220:223], v[138:139], off
	global_load_dwordx4 v[224:227], v[142:143], off offset:16
	global_load_dwordx4 v[228:231], v[142:143], off offset:80
	global_load_dwordx4 v[232:235], v[142:143], off offset:64
	global_load_dwordx4 v[238:241], v[138:139], off offset:64
	global_load_dwordx4 v[242:245], v[138:139], off offset:80
	global_load_dwordx4 v[246:249], v[142:143], off offset:144
	global_load_dwordx4 v[250:253], v[142:143], off offset:128
	global_load_dwordx4 v[162:165], v[138:139], off offset:128
	global_load_dwordx4 v[166:169], v[138:139], off offset:144
	global_load_dwordx4 v[172:175], v[142:143], off offset:208
	global_load_dwordx4 v[176:179], v[142:143], off offset:192
	global_load_dwordx4 v[180:183], v[138:139], off offset:192
	global_load_dwordx4 v[184:187], v[138:139], off offset:208
	global_load_dwordx4 v[188:191], v[142:143], off offset:272
	global_load_dwordx4 v[192:195], v[142:143], off offset:256
	global_load_dwordx4 v[196:199], v[138:139], off offset:256
	global_load_dwordx4 v[200:203], v[138:139], off offset:272
	v_readlane_b32 s48, v237, 1
	v_readlane_b32 s62, v237, 15
	v_readlane_b32 s63, v237, 16
	v_readlane_b32 s56, v237, 9
	v_readlane_b32 s57, v237, 10
	v_lshl_add_u64 v[148:149], s[62:63], 0, v[148:149]
	v_cmp_gt_u32_e32 vcc, 32, v153
	v_readlane_b32 s49, v237, 2
	v_readlane_b32 s50, v237, 3
	v_readlane_b32 s51, v237, 4
	v_readlane_b32 s52, v237, 5
	v_readlane_b32 s53, v237, 6
	v_readlane_b32 s54, v237, 7
	v_readlane_b32 s55, v237, 8
	v_readlane_b32 s58, v237, 11
	v_readlane_b32 s59, v237, 12
	v_readlane_b32 s60, v237, 13
	v_readlane_b32 s61, v237, 14
	s_waitcnt vmcnt(16)
	v_pk_fma_f32 v[128:129], v[112:113], v[212:213], v[220:221]
	v_pk_fma_f32 v[130:131], v[114:115], v[214:215], v[222:223]
	v_pk_fma_f32 v[132:133], v[120:121], v[224:225], v[216:217]
	v_pk_fma_f32 v[134:135], v[122:123], v[226:227], v[218:219]
	global_load_dwordx4 v[212:215], v[142:143], off offset:336
	global_load_dwordx4 v[216:219], v[142:143], off offset:320
	global_load_dwordx4 v[220:223], v[138:139], off offset:320
	global_load_dwordx4 v[224:227], v[138:139], off offset:336
	s_waitcnt vmcnt(16)
	v_pk_fma_f32 v[120:121], v[116:117], v[232:233], v[238:239]
	v_pk_fma_f32 v[124:125], v[124:125], v[228:229], v[242:243]
	v_pk_fma_f32 v[122:123], v[118:119], v[234:235], v[240:241]
	v_pk_fma_f32 v[126:127], v[126:127], v[230:231], v[244:245]
	global_load_dwordx4 v[228:231], v[142:143], off offset:400
	global_load_dwordx4 v[232:235], v[142:143], off offset:384
	global_load_dwordx4 v[238:241], v[138:139], off offset:384
	global_load_dwordx4 v[242:245], v[138:139], off offset:400
	s_waitcnt vmcnt(16)
	v_pk_fma_f32 v[112:113], v[96:97], v[250:251], v[162:163]
	v_pk_fma_f32 v[114:115], v[98:99], v[252:253], v[164:165]
	v_pk_fma_f32 v[116:117], v[104:105], v[246:247], v[166:167]
	v_pk_fma_f32 v[118:119], v[106:107], v[248:249], v[168:169]
	global_load_dwordx4 v[246:249], v[142:143], off offset:464
	global_load_dwordx4 v[250:253], v[142:143], off offset:448
	global_load_dwordx4 v[162:165], v[138:139], off offset:448
	global_load_dwordx4 v[166:169], v[138:139], off offset:464
	s_waitcnt vmcnt(16)
	v_pk_fma_f32 v[104:105], v[100:101], v[176:177], v[180:181]
	v_pk_fma_f32 v[108:109], v[108:109], v[172:173], v[184:185]
	v_pk_fma_f32 v[106:107], v[102:103], v[178:179], v[182:183]
	v_pk_fma_f32 v[110:111], v[110:111], v[174:175], v[186:187]
	s_waitcnt vmcnt(12)
	v_pk_fma_f32 v[96:97], v[80:81], v[192:193], v[196:197]
	v_pk_fma_f32 v[98:99], v[82:83], v[194:195], v[198:199]
	v_pk_fma_f32 v[100:101], v[88:89], v[188:189], v[200:201]
	v_pk_fma_f32 v[102:103], v[90:91], v[190:191], v[202:203]
	s_waitcnt vmcnt(8)
	v_pk_fma_f32 v[88:89], v[84:85], v[216:217], v[220:221]
	v_pk_fma_f32 v[92:93], v[92:93], v[212:213], v[224:225]
	v_pk_fma_f32 v[90:91], v[86:87], v[218:219], v[222:223]
	v_pk_fma_f32 v[94:95], v[94:95], v[214:215], v[226:227]
	s_waitcnt vmcnt(4)
	v_pk_fma_f32 v[80:81], v[64:65], v[232:233], v[238:239]
	v_pk_fma_f32 v[82:83], v[66:67], v[234:235], v[240:241]
	v_pk_fma_f32 v[84:85], v[72:73], v[228:229], v[242:243]
	v_pk_fma_f32 v[86:87], v[74:75], v[230:231], v[244:245]
	s_waitcnt vmcnt(0)
	v_pk_fma_f32 v[72:73], v[68:69], v[250:251], v[162:163]
	v_pk_fma_f32 v[76:77], v[76:77], v[246:247], v[166:167]
	v_pk_fma_f32 v[74:75], v[70:71], v[252:253], v[164:165]
	v_pk_fma_f32 v[78:79], v[78:79], v[248:249], v[168:169]
	v_mov_b64_e32 v[254:255], v[148:149]
	v_or_b32_e32 v138, 32, v140
	v_ashrrev_i32_e32 v139, 31, v138
	v_lshlrev_b64 v[64:65], 10, v[138:139]
	v_lshl_add_u64 v[64:65], v[64:65], 0, v[136:137]
	v_lshlrev_b64 v[148:149], 2, v[64:65]
	v_lshl_add_u64 v[170:171], s[36:37], 0, v[148:149]
	global_load_dwordx4 v[172:175], v[170:171], off offset:16
	global_load_dwordx4 v[176:179], v[170:171], off
	global_load_dwordx4 v[180:183], v[146:147], off
	global_load_dwordx4 v[184:187], v[142:143], off offset:16
	global_load_dwordx4 v[188:191], v[142:143], off offset:80
	global_load_dwordx4 v[192:195], v[142:143], off offset:64
	global_load_dwordx4 v[196:199], v[170:171], off offset:64
	global_load_dwordx4 v[200:203], v[170:171], off offset:80
	global_load_dwordx4 v[212:215], v[142:143], off offset:144
	global_load_dwordx4 v[216:219], v[142:143], off offset:128
	global_load_dwordx4 v[220:223], v[170:171], off offset:128
	global_load_dwordx4 v[224:227], v[170:171], off offset:144
	global_load_dwordx4 v[228:231], v[142:143], off offset:208
	global_load_dwordx4 v[232:235], v[142:143], off offset:192
	global_load_dwordx4 v[238:241], v[170:171], off offset:192
	global_load_dwordx4 v[242:245], v[170:171], off offset:208
	global_load_dwordx4 v[246:249], v[142:143], off offset:272
	global_load_dwordx4 v[250:253], v[142:143], off offset:256
	global_load_dwordx4 v[162:165], v[170:171], off offset:256
	global_load_dwordx4 v[166:169], v[170:171], off offset:272
	v_lshl_add_u64 v[146:147], s[62:63], 0, v[148:149]
	s_waitcnt vmcnt(16)
	v_pk_fma_f32 v[64:65], v[48:49], v[180:181], v[176:177]
	v_pk_fma_f32 v[66:67], v[50:51], v[182:183], v[178:179]
	v_pk_fma_f32 v[68:69], v[56:57], v[184:185], v[172:173]
	v_pk_fma_f32 v[70:71], v[58:59], v[186:187], v[174:175]
	global_load_dwordx4 v[172:175], v[142:143], off offset:336
	global_load_dwordx4 v[176:179], v[142:143], off offset:320
	global_load_dwordx4 v[180:183], v[170:171], off offset:320
	global_load_dwordx4 v[184:187], v[170:171], off offset:336
	s_waitcnt vmcnt(16)
	v_pk_fma_f32 v[56:57], v[52:53], v[192:193], v[196:197]
	v_pk_fma_f32 v[60:61], v[60:61], v[188:189], v[200:201]
	v_pk_fma_f32 v[58:59], v[54:55], v[194:195], v[198:199]
	v_pk_fma_f32 v[62:63], v[62:63], v[190:191], v[202:203]
	global_load_dwordx4 v[188:191], v[142:143], off offset:400
	global_load_dwordx4 v[192:195], v[142:143], off offset:384
	global_load_dwordx4 v[196:199], v[170:171], off offset:384
	global_load_dwordx4 v[200:203], v[170:171], off offset:400
	s_waitcnt vmcnt(16)
	v_pk_fma_f32 v[48:49], v[32:33], v[216:217], v[220:221]
	v_pk_fma_f32 v[50:51], v[34:35], v[218:219], v[222:223]
	v_pk_fma_f32 v[52:53], v[40:41], v[212:213], v[224:225]
	v_pk_fma_f32 v[54:55], v[42:43], v[214:215], v[226:227]
	global_load_dwordx4 v[212:215], v[142:143], off offset:464
	global_load_dwordx4 v[216:219], v[142:143], off offset:448
	global_load_dwordx4 v[220:223], v[170:171], off offset:448
	global_load_dwordx4 v[224:227], v[170:171], off offset:464
	s_waitcnt vmcnt(16)
	v_pk_fma_f32 v[40:41], v[36:37], v[232:233], v[238:239]
	v_pk_fma_f32 v[44:45], v[44:45], v[228:229], v[242:243]
	v_pk_fma_f32 v[42:43], v[38:39], v[234:235], v[240:241]
	v_pk_fma_f32 v[46:47], v[46:47], v[230:231], v[244:245]
	s_waitcnt vmcnt(12)
	v_pk_fma_f32 v[32:33], v[16:17], v[250:251], v[162:163]
	v_pk_fma_f32 v[34:35], v[18:19], v[252:253], v[164:165]
	v_pk_fma_f32 v[36:37], v[24:25], v[246:247], v[166:167]
	v_pk_fma_f32 v[38:39], v[26:27], v[248:249], v[168:169]
	s_waitcnt vmcnt(8)
	v_pk_fma_f32 v[20:21], v[20:21], v[176:177], v[180:181]
	v_pk_fma_f32 v[24:25], v[28:29], v[172:173], v[184:185]
	v_pk_fma_f32 v[22:23], v[22:23], v[178:179], v[182:183]
	v_pk_fma_f32 v[26:27], v[30:31], v[174:175], v[186:187]
	s_waitcnt vmcnt(4)
	v_pk_fma_f32 v[16:17], v[0:1], v[192:193], v[196:197]
	v_pk_fma_f32 v[18:19], v[2:3], v[194:195], v[198:199]
	v_pk_fma_f32 v[8:9], v[8:9], v[188:189], v[200:201]
	v_pk_fma_f32 v[10:11], v[10:11], v[190:191], v[202:203]
	s_waitcnt vmcnt(0)
	v_pk_fma_f32 v[0:1], v[4:5], v[216:217], v[220:221]
	v_pk_fma_f32 v[4:5], v[12:13], v[212:213], v[224:225]
	v_pk_fma_f32 v[2:3], v[6:7], v[218:219], v[222:223]
	v_pk_fma_f32 v[6:7], v[14:15], v[214:215], v[226:227]
	global_store_dwordx4 v[254:255], v[128:131], off
	global_store_dwordx4 v[254:255], v[132:135], off offset:16
	global_store_dwordx4 v[254:255], v[120:123], off offset:64
	global_store_dwordx4 v[254:255], v[124:127], off offset:80
	global_store_dwordx4 v[254:255], v[112:115], off offset:128
	global_store_dwordx4 v[254:255], v[116:119], off offset:144
	global_store_dwordx4 v[254:255], v[104:107], off offset:192
	global_store_dwordx4 v[254:255], v[108:111], off offset:208
	global_store_dwordx4 v[254:255], v[96:99], off offset:256
	global_store_dwordx4 v[254:255], v[100:103], off offset:272
	global_store_dwordx4 v[254:255], v[88:91], off offset:320
	global_store_dwordx4 v[254:255], v[92:95], off offset:336
	global_store_dwordx4 v[254:255], v[80:83], off offset:384
	global_store_dwordx4 v[254:255], v[84:87], off offset:400
	global_store_dwordx4 v[254:255], v[72:75], off offset:448
	global_store_dwordx4 v[254:255], v[76:79], off offset:464
	global_store_dwordx4 v[146:147], v[64:67], off
	global_store_dwordx4 v[146:147], v[68:71], off offset:16
	global_store_dwordx4 v[146:147], v[56:59], off offset:64
	global_store_dwordx4 v[146:147], v[60:63], off offset:80
	global_store_dwordx4 v[146:147], v[48:51], off offset:128
	global_store_dwordx4 v[146:147], v[52:55], off offset:144
	global_store_dwordx4 v[146:147], v[40:43], off offset:192
	global_store_dwordx4 v[146:147], v[44:47], off offset:208
	global_store_dwordx4 v[146:147], v[32:35], off offset:256
	global_store_dwordx4 v[146:147], v[36:39], off offset:272
	global_store_dwordx4 v[146:147], v[20:23], off offset:320
	global_store_dwordx4 v[146:147], v[24:27], off offset:336
	global_store_dwordx4 v[146:147], v[16:19], off offset:384
	global_store_dwordx4 v[146:147], v[8:11], off offset:400
	global_store_dwordx4 v[146:147], v[0:3], off offset:448
	global_store_dwordx4 v[146:147], v[4:7], off offset:464
	v_pk_mul_f32 v[12:13], v[128:129], v[128:129]
	v_pk_mul_f32 v[14:15], v[130:131], v[130:131]
	v_add_f32_e32 v12, v12, v13
	v_add_f32_e32 v12, v14, v12
	v_pk_mul_f32 v[28:29], v[120:121], v[120:121]
	v_add_f32_e32 v12, v15, v12
	v_add_f32_e32 v12, v12, v28
	v_pk_mul_f32 v[30:31], v[122:123], v[122:123]
	v_add_f32_e32 v12, v29, v12
	v_add_f32_e32 v12, v30, v12
	v_pk_mul_f32 v[142:143], v[132:133], v[132:133]
	v_add_f32_e32 v12, v31, v12
	v_add_f32_e32 v12, v142, v12
	v_pk_mul_f32 v[146:147], v[134:135], v[134:135]
	v_add_f32_e32 v12, v143, v12
	v_add_f32_e32 v12, v146, v12
	v_pk_mul_f32 v[148:149], v[124:125], v[124:125]
	v_add_f32_e32 v12, v147, v12
	v_add_f32_e32 v12, v148, v12
	v_pk_mul_f32 v[162:163], v[126:127], v[126:127]
	v_add_f32_e32 v12, v149, v12
	v_add_f32_e32 v12, v162, v12
	v_pk_mul_f32 v[164:165], v[112:113], v[112:113]
	v_add_f32_e32 v12, v163, v12
	v_add_f32_e32 v12, v164, v12
	v_pk_mul_f32 v[166:167], v[114:115], v[114:115]
	v_add_f32_e32 v12, v165, v12
	v_add_f32_e32 v12, v166, v12
	v_pk_mul_f32 v[168:169], v[104:105], v[104:105]
	v_add_f32_e32 v12, v167, v12
	v_add_f32_e32 v12, v168, v12
	v_pk_mul_f32 v[170:171], v[106:107], v[106:107]
	v_add_f32_e32 v12, v169, v12
	v_add_f32_e32 v12, v170, v12
	v_pk_mul_f32 v[172:173], v[116:117], v[116:117]
	v_add_f32_e32 v12, v171, v12
	v_add_f32_e32 v12, v172, v12
	v_pk_mul_f32 v[174:175], v[118:119], v[118:119]
	v_add_f32_e32 v12, v173, v12
	v_add_f32_e32 v12, v174, v12
	v_pk_mul_f32 v[176:177], v[108:109], v[108:109]
	v_add_f32_e32 v12, v175, v12
	v_add_f32_e32 v12, v176, v12
	v_pk_mul_f32 v[178:179], v[110:111], v[110:111]
	v_add_f32_e32 v12, v177, v12
	v_add_f32_e32 v12, v178, v12
	v_pk_mul_f32 v[180:181], v[96:97], v[96:97]
	v_add_f32_e32 v12, v179, v12
	v_add_f32_e32 v12, v180, v12
	v_pk_mul_f32 v[182:183], v[98:99], v[98:99]
	v_add_f32_e32 v12, v181, v12
	v_add_f32_e32 v12, v182, v12
	v_pk_mul_f32 v[184:185], v[88:89], v[88:89]
	v_add_f32_e32 v12, v183, v12
	v_add_f32_e32 v12, v184, v12
	v_pk_mul_f32 v[186:187], v[90:91], v[90:91]
	v_add_f32_e32 v12, v185, v12
	v_add_f32_e32 v12, v186, v12
	v_pk_mul_f32 v[188:189], v[100:101], v[100:101]
	v_add_f32_e32 v12, v187, v12
	v_add_f32_e32 v12, v188, v12
	v_pk_mul_f32 v[190:191], v[102:103], v[102:103]
	v_add_f32_e32 v12, v189, v12
	v_add_f32_e32 v12, v190, v12
	v_pk_mul_f32 v[192:193], v[92:93], v[92:93]
	v_add_f32_e32 v12, v191, v12
	v_add_f32_e32 v12, v192, v12
	v_pk_mul_f32 v[194:195], v[94:95], v[94:95]
	v_add_f32_e32 v12, v193, v12
	v_add_f32_e32 v12, v194, v12
	v_pk_mul_f32 v[196:197], v[80:81], v[80:81]
	v_add_f32_e32 v12, v195, v12
	v_add_f32_e32 v12, v196, v12
	v_pk_mul_f32 v[198:199], v[82:83], v[82:83]
	v_add_f32_e32 v12, v197, v12
	v_add_f32_e32 v12, v198, v12
	v_pk_mul_f32 v[200:201], v[72:73], v[72:73]
	v_add_f32_e32 v12, v199, v12
	v_add_f32_e32 v12, v200, v12
	v_pk_mul_f32 v[202:203], v[74:75], v[74:75]
	v_add_f32_e32 v12, v201, v12
	v_add_f32_e32 v12, v202, v12
	v_pk_mul_f32 v[204:205], v[84:85], v[84:85]
	v_add_f32_e32 v12, v203, v12
	v_add_f32_e32 v12, v204, v12
	v_pk_mul_f32 v[206:207], v[86:87], v[86:87]
	v_add_f32_e32 v12, v205, v12
	v_add_f32_e32 v12, v206, v12
	v_pk_mul_f32 v[208:209], v[76:77], v[76:77]
	v_add_f32_e32 v12, v207, v12
	v_add_f32_e32 v12, v208, v12
	v_pk_mul_f32 v[210:211], v[78:79], v[78:79]
	v_add_f32_e32 v12, v209, v12
	v_add_f32_e32 v12, v210, v12
	v_add_f32_e32 v14, v211, v12
	ds_bpermute_b32 v15, v145, v14
	s_lshl_b64 s[56:57], s[82:83], 2
	s_add_u32 s56, s0, s56
	s_addc_u32 s57, s1, s57
	v_lshlrev_b32_e32 v12, 2, v152
	v_mov_b32_e32 v13, v137
	v_lshl_add_u64 v[12:13], s[56:57], 0, v[12:13]
	s_and_saveexec_b64 s[56:57], vcc
	s_cbranch_execz .LBB0_392
	s_waitcnt lgkmcnt(0)
	v_add_f32_e32 v14, v14, v15
	global_atomic_add_f32 v[12:13], v14, off
